# sample-unit epilogues of residual GEMMs (phases 4,9,12) batched loads; retb output stage loads batched
# baseline (speedup 1.0000x reference)
.LBB0_899:
	v_mov_b32_e32 v4, v44
	v_mov_b32_e32 v5, v40
	v_mov_b32_e32 v6, v45
	v_mov_b32_e32 v7, v41
	v_pk_add_f32 v[4:5], v[4:5], v[6:7]
	v_mov_b32_e32 v6, v46
	v_mov_b32_e32 v7, v42
	v_mov_b32_e32 v8, v47
	v_mov_b32_e32 v9, v43
	v_pk_add_f32 v[6:7], v[6:7], v[8:9]
	v_mov_b32_e32 v8, v36
	v_pk_add_f32 v[4:5], v[4:5], v[6:7]
	v_mov_b32_e32 v6, v37
	v_mov_b32_e32 v7, v38
	v_mov_b32_e32 v9, v39
	v_pk_add_f32 v[6:7], v[6:7], v[8:9]
	v_add_f32_e32 v5, 0, v5
	v_pk_add_f32 v[6:7], v[6:7], v[6:7] op_sel_hi:[0,1]
	v_add_f32_e32 v5, v4, v5
	v_add_f32_e32 v9, v32, v33
	v_add_f32_e32 v11, v34, v35
	v_mov_b32_e32 v8, v28
	v_mov_b32_e32 v10, v29
	v_mov_b32_e32 v6, v30
	v_mov_b32_e32 v4, v31
	v_pk_add_f32 v[8:9], v[8:9], v[10:11]
	v_pk_add_f32 v[4:5], v[6:7], v[4:5]
	v_mov_b32_e32 v6, v25
	v_pk_add_f32 v[4:5], v[8:9], v[4:5]
	v_mov_b32_e32 v7, v26
	v_mov_b32_e32 v8, v24
	v_mov_b32_e32 v9, v27
	v_pk_add_f32 v[6:7], v[6:7], v[8:9]
	v_pk_add_f32 v[4:5], v[4:5], v[4:5] op_sel_hi:[0,1]
	v_pk_add_f32 v[6:7], v[6:7], v[6:7] op_sel_hi:[0,1]
	v_add_f32_e32 v9, v20, v21
	v_add_f32_e32 v11, v22, v23
	v_mov_b32_e32 v8, v0
	v_mov_b32_e32 v10, v1
	v_mov_b32_e32 v6, v2
	v_mov_b32_e32 v4, v3
	v_pk_add_f32 v[8:9], v[8:9], v[10:11]
	v_pk_add_f32 v[4:5], v[6:7], v[4:5]
	v_and_b32_e32 v6, 64, v126
	v_pk_add_f32 v[4:5], v[8:9], v[4:5]
	v_add_u32_e32 v6, 64, v6
	v_add_f32_e32 v4, v4, v5
	v_xor_b32_e32 v5, 16, v126
	v_cmp_lt_i32_e32 vcc, v5, v6
	s_lshl_b32 s8, s0, 1
	s_lshl_b32 s0, s0, 2
	v_cndmask_b32_e32 v5, v126, v5, vcc
	v_lshlrev_b32_e32 v52, 2, v5
	ds_bpermute_b32 v5, v52, v4
	s_mov_b32 s1, s9
	s_add_i32 s10, s10, s34
	s_cmpk_gt_i32 s10, 0x1ff
	s_waitcnt lgkmcnt(0)
	v_add_f32_e32 v4, v4, v5
	v_xor_b32_e32 v5, 32, v126
	v_cmp_lt_i32_e32 vcc, v5, v6
	s_nop 1
	v_cndmask_b32_e32 v5, v126, v5, vcc
	v_lshlrev_b32_e32 v53, 2, v5
	ds_bpermute_b32 v5, v53, v4
	s_waitcnt lgkmcnt(0)
	v_add_f32_e32 v54, v4, v5
	v_fmamk_f32 v41, v54, 0xbc000000, v41
	v_fmamk_f32 v19, v54, 0xbc000000, v45
	v_fmamk_f32 v43, v54, 0xbc000000, v43
	v_fmamk_f32 v40, v54, 0xbc000000, v40
	v_fmamk_f32 v17, v54, 0xbc000000, v47
	v_fmamk_f32 v18, v54, 0xbc000000, v44
	v_mov_b32_e32 v6, v41
	v_mov_b32_e32 v7, v19
	v_fmamk_f32 v42, v54, 0xbc000000, v42
	v_fmamk_f32 v16, v54, 0xbc000000, v46
	v_mov_b32_e32 v4, v40
	v_mov_b32_e32 v5, v18
	v_pk_mul_f32 v[6:7], v[6:7], v[6:7]
	v_mov_b32_e32 v8, v43
	v_mov_b32_e32 v9, v17
	v_pk_fma_f32 v[4:5], v[4:5], v[4:5], v[6:7]
	v_mov_b32_e32 v6, v42
	v_mov_b32_e32 v7, v16
	v_pk_mul_f32 v[8:9], v[8:9], v[8:9]
	v_fmamk_f32 v37, v54, 0xbc000000, v37
	v_pk_fma_f32 v[6:7], v[6:7], v[6:7], v[8:9]
	v_fmamk_f32 v36, v54, 0xbc000000, v36
	v_pk_add_f32 v[4:5], v[4:5], v[6:7]
	v_fmamk_f32 v39, v54, 0xbc000000, v39
	v_fmamk_f32 v38, v54, 0xbc000000, v38
	v_pk_add_f32 v[4:5], v[4:5], v[4:5] op_sel_hi:[0,1]
	v_pk_mul_f32 v[6:7], v[38:39], v[38:39]
	v_pk_mul_f32 v[8:9], v[36:37], v[36:37]
	v_fmamk_f32 v12, v54, 0xbc000000, v32
	v_pk_mov_b32 v[10:11], v[8:9], v[6:7] op_sel:[1,0]
	v_mov_b32_e32 v9, v7
	v_fmamk_f32 v13, v54, 0xbc000000, v33
	v_fmamk_f32 v14, v54, 0xbc000000, v34
	v_mul_f32_e32 v4, v12, v12
	v_pk_add_f32 v[6:7], v[10:11], v[8:9]
	v_fmamk_f32 v15, v54, 0xbc000000, v35
	v_pk_fma_f32 v[32:33], v[12:13], v[12:13], v[4:5] op_sel_hi:[1,1,0]
	v_mul_f32_e32 v4, v14, v14
	v_pk_add_f32 v[6:7], v[6:7], v[6:7] op_sel_hi:[0,1]
	v_pk_fma_f32 v[34:35], v[14:15], v[14:15], v[4:5] op_sel_hi:[1,1,0]
	v_fmamk_f32 v9, v54, 0xbc000000, v31
	v_fmamk_f32 v8, v54, 0xbc000000, v30
	v_fmamk_f32 v11, v54, 0xbc000000, v29
	v_fmamk_f32 v10, v54, 0xbc000000, v28
	v_mul_f32_e32 v32, v10, v10
	v_mul_f32_e32 v34, v11, v11
	v_mul_f32_e32 v6, v8, v8
	v_mul_f32_e32 v4, v9, v9
	v_pk_add_f32 v[28:29], v[32:33], v[34:35]
	v_pk_add_f32 v[4:5], v[6:7], v[4:5]
	v_fmamk_f32 v7, v54, 0xbc000000, v27
	v_pk_add_f32 v[4:5], v[28:29], v[4:5]
	v_fmamk_f32 v6, v54, 0xbc000000, v26
	v_pk_add_f32 v[30:31], v[4:5], v[4:5] op_sel_hi:[0,1]
	v_fmamk_f32 v5, v54, 0xbc000000, v25
	v_fmamk_f32 v4, v54, 0xbc000000, v24
	v_pk_mul_f32 v[24:25], v[6:7], v[6:7]
	v_pk_mul_f32 v[32:33], v[4:5], v[4:5]
	v_lshlrev_b32_e32 v46, 1, v64
	v_pk_mov_b32 v[34:35], v[32:33], v[24:25] op_sel:[1,0]
	v_mov_b32_e32 v33, v25
	v_lshl_add_u64 v[24:25], s[48:49], 0, v[74:75]
	v_lshl_add_u64 v[44:45], v[24:25], 0, s[8:9]
	v_mov_b32_e32 v47, v61
	v_lshl_add_u64 v[24:25], v[66:67], 0, s[0:1]
	v_lshl_add_u64 v[44:45], v[44:45], 0, v[46:47]
	global_load_dwordx4 v[180:183], v[24:25], off
	global_load_dwordx2 v[212:213], v[44:45], off
	global_load_dwordx4 v[184:187], v[24:25], off offset:64
	global_load_dwordx2 v[214:215], v[44:45], off offset:32
	global_load_dwordx4 v[188:191], v[24:25], off offset:128
	global_load_dwordx2 v[216:217], v[44:45], off offset:64
	global_load_dwordx4 v[192:195], v[24:25], off offset:192
	global_load_dwordx2 v[218:219], v[44:45], off offset:96
	global_load_dwordx4 v[196:199], v[24:25], off offset:256
	global_load_dwordx2 v[220:221], v[44:45], off offset:128
	global_load_dwordx4 v[200:203], v[24:25], off offset:320
	global_load_dwordx2 v[222:223], v[44:45], off offset:160
	global_load_dwordx4 v[204:207], v[24:25], off offset:384
	global_load_dwordx2 v[224:225], v[44:45], off offset:192
	global_load_dwordx4 v[208:211], v[24:25], off offset:448
	global_load_dwordx2 v[226:227], v[44:45], off offset:224
	v_pk_add_f32 v[32:33], v[34:35], v[32:33]
	v_fmamk_f32 v34, v54, 0xbc000000, v20
	v_fmamk_f32 v35, v54, 0xbc000000, v21
	v_mul_f32_e32 v20, v34, v34
	v_fmamk_f32 v50, v54, 0xbc000000, v22
	v_pk_fma_f32 v[20:21], v[34:35], v[34:35], v[20:21] op_sel_hi:[1,1,0]
	v_fmamk_f32 v51, v54, 0xbc000000, v23
	v_mul_f32_e32 v20, v50, v50
	v_pk_add_f32 v[32:33], v[32:33], v[32:33] op_sel_hi:[0,1]
	v_pk_fma_f32 v[22:23], v[50:51], v[50:51], v[20:21] op_sel_hi:[1,1,0]
	v_fmamk_f32 v3, v54, 0xbc000000, v3
	v_fmamk_f32 v2, v54, 0xbc000000, v2
	v_fmamk_f32 v1, v54, 0xbc000000, v1
	v_fmac_f32_e32 v0, 0xbc000000, v54
	v_mul_f32_e32 v20, v0, v0
	v_mul_f32_e32 v22, v1, v1
	v_mul_f32_e32 v32, v2, v2
	v_mul_f32_e32 v30, v3, v3
	v_pk_add_f32 v[20:21], v[20:21], v[22:23]
	v_pk_add_f32 v[22:23], v[32:33], v[30:31]
	s_nop 0
	v_pk_add_f32 v[20:21], v[20:21], v[22:23]
	s_nop 0
	v_add_f32_e32 v20, v20, v21
	ds_bpermute_b32 v21, v52, v20
	s_waitcnt lgkmcnt(0)
	v_add_f32_e32 v20, v20, v21
	ds_bpermute_b32 v21, v53, v20
	s_waitcnt lgkmcnt(0)
	v_add_f32_e32 v20, v20, v21
	v_fmamk_f32 v20, v20, 0x3c000000, v121
	v_mul_f32_e32 v21, 0x4f800000, v20
	v_cmp_gt_f32_e32 vcc, s6, v20
	s_nop 1
	v_cndmask_b32_e32 v20, v20, v21, vcc
	v_sqrt_f32_e32 v21, v20
	s_nop 0
	v_add_u32_e32 v22, -1, v21
	v_fma_f32 v23, -v22, v21, v20
	v_cmp_ge_f32_e64 s[0:1], 0, v23
	v_add_u32_e32 v23, 1, v21
	s_nop 0
	v_cndmask_b32_e64 v22, v21, v22, s[0:1]
	v_fma_f32 v21, -v23, v21, v20
	v_cmp_lt_f32_e64 s[0:1], 0, v21
	s_nop 1
	v_cndmask_b32_e64 v21, v22, v23, s[0:1]
	v_mul_f32_e32 v22, 0x37800000, v21
	v_cndmask_b32_e32 v21, v21, v22, vcc
	v_cmp_class_f32_e32 vcc, v20, v122
	s_nop 1
	v_cndmask_b32_e32 v20, v21, v20, vcc
	v_div_scale_f32 v21, s[0:1], v20, v20, 1.0
	v_rcp_f32_e32 v22, v21
	s_nop 0
	v_fma_f32 v23, -v21, v22, 1.0
	v_fmac_f32_e32 v22, v23, v22
	v_div_scale_f32 v23, vcc, 1.0, v20, 1.0
	v_mul_f32_e32 v30, v23, v22
	v_fma_f32 v31, -v21, v30, v23
	v_fmac_f32_e32 v30, v31, v22
	v_fma_f32 v21, -v21, v30, v23
	v_div_fmas_f32 v21, v21, v22, v30
	v_div_fixup_f32 v30, v21, v20, 1.0
	v_lshlrev_b64 v[20:21], 11, v[60:61]
	v_lshl_add_u64 v[20:21], s[24:25], 0, v[20:21]
	v_lshl_add_u64 v[20:21], v[20:21], 0, s[8:9]
	v_lshl_add_u64 v[32:33], v[20:21], 0, v[46:47]
	v_pk_mul_f32 v[20:21], v[40:41], v[30:31] op_sel_hi:[1,0]
	v_pk_mul_f32 v[22:23], v[42:43], v[30:31] op_sel_hi:[1,0]
	v_pk_mul_f32 v[18:19], v[18:19], v[30:31] op_sel_hi:[1,0]
	v_pk_mul_f32 v[16:17], v[16:17], v[30:31] op_sel_hi:[1,0]
	v_pk_mul_f32 v[36:37], v[36:37], v[30:31] op_sel_hi:[1,0]
	v_pk_mul_f32 v[38:39], v[38:39], v[30:31] op_sel_hi:[1,0]
	v_pk_mul_f32 v[12:13], v[12:13], v[30:31] op_sel_hi:[1,0]
	v_pk_mul_f32 v[14:15], v[14:15], v[30:31] op_sel_hi:[1,0]
	v_pk_mul_f32 v[10:11], v[10:11], v[30:31] op_sel_hi:[1,0]
	v_pk_mul_f32 v[8:9], v[8:9], v[30:31] op_sel_hi:[1,0]
	v_pk_mul_f32 v[4:5], v[4:5], v[30:31] op_sel_hi:[1,0]
	v_pk_mul_f32 v[6:7], v[6:7], v[30:31] op_sel_hi:[1,0]
	v_pk_mul_f32 v[34:35], v[34:35], v[30:31] op_sel_hi:[1,0]
	v_pk_mul_f32 v[50:51], v[50:51], v[30:31] op_sel_hi:[1,0]
	v_pk_mul_f32 v[0:1], v[0:1], v[30:31] op_sel_hi:[1,0]
	v_pk_mul_f32 v[2:3], v[2:3], v[30:31] op_sel_hi:[1,0]
	s_waitcnt vmcnt(14)
	v_pk_mul_f32 v[20:21], v[180:181], v[20:21]
	v_pk_mul_f32 v[22:23], v[182:183], v[22:23]
	v_lshlrev_b32_e32 v244, 16, v212
	v_and_b32_e32 v245, 0xffff0000, v212
	v_lshlrev_b32_e32 v246, 16, v213
	v_and_b32_e32 v247, 0xffff0000, v213
	v_mul_f32_e32 v20, v20, v244
	v_mul_f32_e32 v21, v21, v245
	v_mul_f32_e32 v22, v22, v246
	v_mul_f32_e32 v23, v23, v247
	v_cvt_pk_bf16_f32 v228, v20, v21
	v_cvt_pk_bf16_f32 v229, v22, v23
	global_store_dwordx2 v[32:33], v[228:229], off
	s_waitcnt vmcnt(13)
	v_pk_mul_f32 v[18:19], v[184:185], v[18:19]
	v_pk_mul_f32 v[16:17], v[186:187], v[16:17]
	v_lshlrev_b32_e32 v244, 16, v214
	v_and_b32_e32 v245, 0xffff0000, v214
	v_lshlrev_b32_e32 v246, 16, v215
	v_and_b32_e32 v247, 0xffff0000, v215
	v_mul_f32_e32 v18, v18, v244
	v_mul_f32_e32 v19, v19, v245
	v_mul_f32_e32 v16, v16, v246
	v_mul_f32_e32 v17, v17, v247
	v_cvt_pk_bf16_f32 v230, v18, v19
	v_cvt_pk_bf16_f32 v231, v16, v17
	global_store_dwordx2 v[32:33], v[230:231], off offset:32
	s_waitcnt vmcnt(12)
	v_pk_mul_f32 v[36:37], v[188:189], v[36:37]
	v_pk_mul_f32 v[38:39], v[190:191], v[38:39]
	v_lshlrev_b32_e32 v244, 16, v216
	v_and_b32_e32 v245, 0xffff0000, v216
	v_lshlrev_b32_e32 v246, 16, v217
	v_and_b32_e32 v247, 0xffff0000, v217
	v_mul_f32_e32 v36, v36, v244
	v_mul_f32_e32 v37, v37, v245
	v_mul_f32_e32 v38, v38, v246
	v_mul_f32_e32 v39, v39, v247
	v_cvt_pk_bf16_f32 v232, v36, v37
	v_cvt_pk_bf16_f32 v233, v38, v39
	global_store_dwordx2 v[32:33], v[232:233], off offset:64
	s_waitcnt vmcnt(11)
	v_pk_mul_f32 v[12:13], v[192:193], v[12:13]
	v_pk_mul_f32 v[14:15], v[194:195], v[14:15]
	v_lshlrev_b32_e32 v244, 16, v218
	v_and_b32_e32 v245, 0xffff0000, v218
	v_lshlrev_b32_e32 v246, 16, v219
	v_and_b32_e32 v247, 0xffff0000, v219
	v_mul_f32_e32 v12, v12, v244
	v_mul_f32_e32 v13, v13, v245
	v_mul_f32_e32 v14, v14, v246
	v_mul_f32_e32 v15, v15, v247
	v_cvt_pk_bf16_f32 v234, v12, v13
	v_cvt_pk_bf16_f32 v235, v14, v15
	global_store_dwordx2 v[32:33], v[234:235], off offset:96
	s_waitcnt vmcnt(10)
	v_pk_mul_f32 v[10:11], v[196:197], v[10:11]
	v_pk_mul_f32 v[8:9], v[198:199], v[8:9]
	v_lshlrev_b32_e32 v244, 16, v220
	v_and_b32_e32 v245, 0xffff0000, v220
	v_lshlrev_b32_e32 v246, 16, v221
	v_and_b32_e32 v247, 0xffff0000, v221
	v_mul_f32_e32 v10, v10, v244
	v_mul_f32_e32 v11, v11, v245
	v_mul_f32_e32 v8, v8, v246
	v_mul_f32_e32 v9, v9, v247
	v_cvt_pk_bf16_f32 v236, v10, v11
	v_cvt_pk_bf16_f32 v237, v8, v9
	global_store_dwordx2 v[32:33], v[236:237], off offset:128
	s_waitcnt vmcnt(9)
	v_pk_mul_f32 v[4:5], v[200:201], v[4:5]
	v_pk_mul_f32 v[6:7], v[202:203], v[6:7]
	v_lshlrev_b32_e32 v244, 16, v222
	v_and_b32_e32 v245, 0xffff0000, v222
	v_lshlrev_b32_e32 v246, 16, v223
	v_and_b32_e32 v247, 0xffff0000, v223
	v_mul_f32_e32 v4, v4, v244
	v_mul_f32_e32 v5, v5, v245
	v_mul_f32_e32 v6, v6, v246
	v_mul_f32_e32 v7, v7, v247
	v_cvt_pk_bf16_f32 v238, v4, v5
	v_cvt_pk_bf16_f32 v239, v6, v7
	global_store_dwordx2 v[32:33], v[238:239], off offset:160
	s_waitcnt vmcnt(8)
	v_pk_mul_f32 v[34:35], v[204:205], v[34:35]
	v_pk_mul_f32 v[50:51], v[206:207], v[50:51]
	v_lshlrev_b32_e32 v244, 16, v224
	v_and_b32_e32 v245, 0xffff0000, v224
	v_lshlrev_b32_e32 v246, 16, v225
	v_and_b32_e32 v247, 0xffff0000, v225
	v_mul_f32_e32 v34, v34, v244
	v_mul_f32_e32 v35, v35, v245
	v_mul_f32_e32 v50, v50, v246
	v_mul_f32_e32 v51, v51, v247
	v_cvt_pk_bf16_f32 v240, v34, v35
	v_cvt_pk_bf16_f32 v241, v50, v51
	global_store_dwordx2 v[32:33], v[240:241], off offset:192
	s_waitcnt vmcnt(7)
	v_pk_mul_f32 v[0:1], v[208:209], v[0:1]
	v_pk_mul_f32 v[2:3], v[210:211], v[2:3]
	v_lshlrev_b32_e32 v244, 16, v226
	v_and_b32_e32 v245, 0xffff0000, v226
	v_lshlrev_b32_e32 v246, 16, v227
	v_and_b32_e32 v247, 0xffff0000, v227
	v_mul_f32_e32 v0, v0, v244
	v_mul_f32_e32 v1, v1, v245
	v_mul_f32_e32 v2, v2, v246
	v_mul_f32_e32 v3, v3, v247
	v_cvt_pk_bf16_f32 v242, v0, v1
	v_cvt_pk_bf16_f32 v243, v2, v3
	global_store_dwordx2 v[32:33], v[242:243], off offset:224
	s_barrier
	s_cbranch_scc1 .LBB0_896

.LBB0_1081:
	v_lshl_or_b32 v128, s52, 8, v168
	s_mov_b64 s[6:7], -1
	s_cmp_lt_i32 s48, 64
	v_ashrrev_i32_e32 v129, 31, v128
	s_cbranch_scc1 .LBB0_1084
	s_lshl_b32 s6, s48, 8
	s_add_i32 s6, s6, s43
	v_or_b32_e32 v174, s6, v164
	v_add_u32_e32 v142, 0xffffc000, v174
	v_lshrrev_b32_e32 v130, 2, v142
	v_or_b32_e32 v130, 8, v130
	v_mov_b64_e32 v[132:133], s[12:13]
	v_mad_i64_i32 v[134:135], s[20:21], v130, s66, v[132:133]
	v_lshlrev_b64 v[130:131], 2, v[128:129]
	v_lshl_add_u64 v[172:173], v[134:135], 0, v[130:131]
	s_ashr_i32 s51, s50, 31
	s_lshl_b64 s[20:21], s[50:51], 21
	s_add_u32 s50, s26, s20
	s_addc_u32 s51, s27, s21
	v_ashrrev_i32_e32 v143, 31, v142
	v_lshlrev_b64 v[142:143], 12, v[142:143]
	v_lshl_add_u64 v[142:143], s[50:51], 0, v[142:143]
	v_lshl_add_u64 v[142:143], v[142:143], 0, v[130:131]
	global_load_dwordx4 v[180:183], v[172:173], off
	global_load_dwordx4 v[184:187], v[172:173], off offset:16
	global_load_dwordx4 v[188:191], v[172:173], off offset:512
	global_load_dwordx4 v[192:195], v[172:173], off offset:528
	s_mov_b64 s[20:21], 0x24000
	v_lshl_add_u64 v[136:137], v[172:173], 0, s[20:21]
	global_load_dwordx4 v[196:199], v[136:137], off
	global_load_dwordx4 v[200:203], v[136:137], off offset:16
	global_load_dwordx4 v[204:207], v[136:137], off offset:512
	global_load_dwordx4 v[208:211], v[136:137], off offset:528
	s_mov_b64 s[20:21], 0x48000
	v_lshl_add_u64 v[136:137], v[172:173], 0, s[20:21]
	global_load_dwordx4 v[212:215], v[136:137], off
	global_load_dwordx4 v[216:219], v[136:137], off offset:16
	global_load_dwordx4 v[228:231], v[136:137], off offset:512
	global_load_dwordx4 v[232:235], v[136:137], off offset:528
	s_mov_b64 s[20:21], 0x6c000
	v_lshl_add_u64 v[136:137], v[172:173], 0, s[20:21]
	global_load_dwordx4 v[236:239], v[136:137], off
	global_load_dwordx4 v[240:243], v[136:137], off offset:16
	global_load_dwordx4 v[244:247], v[136:137], off offset:512
	global_load_dwordx4 v[248:251], v[136:137], off offset:528
	s_waitcnt vmcnt(12)
	v_pk_mul_f32 v[180:181], v[124:125], v[180:181]
	v_pk_mul_f32 v[182:183], v[126:127], v[182:183]
	v_pk_mul_f32 v[184:185], v[120:121], v[184:185]
	v_pk_mul_f32 v[186:187], v[122:123], v[186:187]
	v_pk_mul_f32 v[188:189], v[108:109], v[188:189]
	v_pk_mul_f32 v[190:191], v[110:111], v[190:191]
	v_pk_mul_f32 v[192:193], v[104:105], v[192:193]
	v_pk_mul_f32 v[194:195], v[106:107], v[194:195]
	global_store_dwordx4 v[142:143], v[180:183], off
	global_store_dwordx4 v[142:143], v[184:187], off offset:16
	global_store_dwordx4 v[142:143], v[188:191], off offset:512
	global_store_dwordx4 v[142:143], v[192:195], off offset:528
	s_mov_b64 s[20:21], 0x120000
	v_lshl_add_u64 v[136:137], v[172:173], 0, s[20:21]
	global_load_dwordx4 v[124:127], v[136:137], off
	global_load_dwordx4 v[120:123], v[136:137], off offset:16
	global_load_dwordx4 v[108:111], v[136:137], off offset:512
	global_load_dwordx4 v[104:107], v[136:137], off offset:528
	s_waitcnt vmcnt(16)
	v_pk_mul_f32 v[196:197], v[116:117], v[196:197]
	v_pk_mul_f32 v[198:199], v[118:119], v[198:199]
	v_pk_mul_f32 v[200:201], v[112:113], v[200:201]
	v_pk_mul_f32 v[202:203], v[114:115], v[202:203]
	v_pk_mul_f32 v[204:205], v[100:101], v[204:205]
	v_pk_mul_f32 v[206:207], v[102:103], v[206:207]
	v_pk_mul_f32 v[208:209], v[96:97], v[208:209]
	v_pk_mul_f32 v[210:211], v[98:99], v[210:211]
	s_mov_b64 s[20:21], 0x10000
	v_lshl_add_u64 v[138:139], v[142:143], 0, s[20:21]
	global_store_dwordx4 v[138:139], v[196:199], off
	global_store_dwordx4 v[138:139], v[200:203], off offset:16
	global_store_dwordx4 v[138:139], v[204:207], off offset:512
	global_store_dwordx4 v[138:139], v[208:211], off offset:528
	s_mov_b64 s[20:21], 0x144000
	v_lshl_add_u64 v[136:137], v[172:173], 0, s[20:21]
	global_load_dwordx4 v[116:119], v[136:137], off
	global_load_dwordx4 v[112:115], v[136:137], off offset:16
	global_load_dwordx4 v[100:103], v[136:137], off offset:512
	global_load_dwordx4 v[96:99], v[136:137], off offset:528
	s_waitcnt vmcnt(20)
	v_pk_mul_f32 v[212:213], v[92:93], v[212:213]
	v_pk_mul_f32 v[214:215], v[94:95], v[214:215]
	v_pk_mul_f32 v[216:217], v[88:89], v[216:217]
	v_pk_mul_f32 v[218:219], v[90:91], v[218:219]
	v_pk_mul_f32 v[228:229], v[76:77], v[228:229]
	v_pk_mul_f32 v[230:231], v[78:79], v[230:231]
	v_pk_mul_f32 v[232:233], v[72:73], v[232:233]
	v_pk_mul_f32 v[234:235], v[74:75], v[234:235]
	s_mov_b64 s[20:21], 0x20000
	v_lshl_add_u64 v[138:139], v[142:143], 0, s[20:21]
	global_store_dwordx4 v[138:139], v[212:215], off
	global_store_dwordx4 v[138:139], v[216:219], off offset:16
	global_store_dwordx4 v[138:139], v[228:231], off offset:512
	global_store_dwordx4 v[138:139], v[232:235], off offset:528
	s_mov_b64 s[20:21], 0x168000
	v_lshl_add_u64 v[136:137], v[172:173], 0, s[20:21]
	global_load_dwordx4 v[92:95], v[136:137], off
	global_load_dwordx4 v[88:91], v[136:137], off offset:16
	global_load_dwordx4 v[76:79], v[136:137], off offset:512
	global_load_dwordx4 v[72:75], v[136:137], off offset:528
	s_waitcnt vmcnt(24)
	v_pk_mul_f32 v[236:237], v[84:85], v[236:237]
	v_pk_mul_f32 v[238:239], v[86:87], v[238:239]
	v_pk_mul_f32 v[240:241], v[80:81], v[240:241]
	v_pk_mul_f32 v[242:243], v[82:83], v[242:243]
	v_pk_mul_f32 v[244:245], v[68:69], v[244:245]
	v_pk_mul_f32 v[246:247], v[70:71], v[246:247]
	v_pk_mul_f32 v[248:249], v[64:65], v[248:249]
	v_pk_mul_f32 v[250:251], v[66:67], v[250:251]
	s_mov_b64 s[20:21], 0x30000
	v_lshl_add_u64 v[138:139], v[142:143], 0, s[20:21]
	global_store_dwordx4 v[138:139], v[236:239], off
	global_store_dwordx4 v[138:139], v[240:243], off offset:16
	global_store_dwordx4 v[138:139], v[244:247], off offset:512
	global_store_dwordx4 v[138:139], v[248:251], off offset:528
	s_mov_b64 s[20:21], 0x18c000
	v_lshl_add_u64 v[136:137], v[172:173], 0, s[20:21]
	global_load_dwordx4 v[84:87], v[136:137], off
	global_load_dwordx4 v[80:83], v[136:137], off offset:16
	global_load_dwordx4 v[68:71], v[136:137], off offset:512
	global_load_dwordx4 v[64:67], v[136:137], off offset:528
	s_waitcnt vmcnt(24)
	v_pk_mul_f32 v[124:125], v[60:61], v[124:125]
	v_pk_mul_f32 v[126:127], v[62:63], v[126:127]
	v_pk_mul_f32 v[120:121], v[56:57], v[120:121]
	v_pk_mul_f32 v[122:123], v[58:59], v[122:123]
	v_pk_mul_f32 v[108:109], v[44:45], v[108:109]
	v_pk_mul_f32 v[110:111], v[46:47], v[110:111]
	v_pk_mul_f32 v[104:105], v[40:41], v[104:105]
	v_pk_mul_f32 v[106:107], v[42:43], v[106:107]
	s_mov_b64 s[20:21], 0x80000
	v_lshl_add_u64 v[138:139], v[142:143], 0, s[20:21]
	global_store_dwordx4 v[138:139], v[124:127], off
	global_store_dwordx4 v[138:139], v[120:123], off offset:16
	global_store_dwordx4 v[138:139], v[108:111], off offset:512
	global_store_dwordx4 v[138:139], v[104:107], off offset:528
	s_waitcnt vmcnt(20)
	v_pk_mul_f32 v[116:117], v[52:53], v[116:117]
	v_pk_mul_f32 v[118:119], v[54:55], v[118:119]
	v_pk_mul_f32 v[112:113], v[48:49], v[112:113]
	v_pk_mul_f32 v[114:115], v[50:51], v[114:115]
	v_pk_mul_f32 v[100:101], v[36:37], v[100:101]
	v_pk_mul_f32 v[102:103], v[38:39], v[102:103]
	v_pk_mul_f32 v[96:97], v[32:33], v[96:97]
	v_pk_mul_f32 v[98:99], v[34:35], v[98:99]
	s_mov_b64 s[20:21], 0x90000
	v_lshl_add_u64 v[138:139], v[142:143], 0, s[20:21]
	global_store_dwordx4 v[138:139], v[116:119], off
	global_store_dwordx4 v[138:139], v[112:115], off offset:16
	global_store_dwordx4 v[138:139], v[100:103], off offset:512
	global_store_dwordx4 v[138:139], v[96:99], off offset:528
	s_waitcnt vmcnt(16)
	v_pk_mul_f32 v[92:93], v[28:29], v[92:93]
	v_pk_mul_f32 v[94:95], v[30:31], v[94:95]
	v_pk_mul_f32 v[88:89], v[24:25], v[88:89]
	v_pk_mul_f32 v[90:91], v[26:27], v[90:91]
	v_pk_mul_f32 v[76:77], v[20:21], v[76:77]
	v_pk_mul_f32 v[78:79], v[22:23], v[78:79]
	v_pk_mul_f32 v[72:73], v[12:13], v[72:73]
	v_pk_mul_f32 v[74:75], v[14:15], v[74:75]
	s_mov_b64 s[20:21], 0xa0000
	v_lshl_add_u64 v[138:139], v[142:143], 0, s[20:21]
	global_store_dwordx4 v[138:139], v[92:95], off
	global_store_dwordx4 v[138:139], v[88:91], off offset:16
	global_store_dwordx4 v[138:139], v[76:79], off offset:512
	global_store_dwordx4 v[138:139], v[72:75], off offset:528
	s_waitcnt vmcnt(12)
	v_pk_mul_f32 v[84:85], v[16:17], v[84:85]
	v_pk_mul_f32 v[86:87], v[18:19], v[86:87]
	v_pk_mul_f32 v[80:81], v[8:9], v[80:81]
	v_pk_mul_f32 v[82:83], v[10:11], v[82:83]
	v_pk_mul_f32 v[68:69], v[4:5], v[68:69]
	v_pk_mul_f32 v[70:71], v[6:7], v[70:71]
	v_pk_mul_f32 v[64:65], v[0:1], v[64:65]
	v_pk_mul_f32 v[66:67], v[2:3], v[66:67]
	s_mov_b64 s[20:21], 0xb0000
	v_lshl_add_u64 v[138:139], v[142:143], 0, s[20:21]
	global_store_dwordx4 v[138:139], v[84:87], off
	global_store_dwordx4 v[138:139], v[80:83], off offset:16
	global_store_dwordx4 v[138:139], v[68:71], off offset:512
	global_store_dwordx4 v[138:139], v[64:67], off offset:528
	s_cbranch_execz .LBB0_1085

.LBB0_1326:
	v_lshl_or_b32 v146, s37, 8, v170
	s_mov_b64 s[6:7], -1
	s_cmp_lt_i32 s64, 64
	v_ashrrev_i32_e32 v147, 31, v146
	s_cbranch_scc1 .LBB0_1329
	s_lshl_b32 s6, s64, 8
	s_add_i32 s6, s6, s47
	v_or_b32_e32 v186, s6, v166
	v_add_u32_e32 v164, 0xffffc000, v186
	v_lshrrev_b32_e32 v148, 2, v164
	v_or_b32_e32 v148, 8, v148
	v_mov_b64_e32 v[150:151], s[12:13]
	v_mad_i64_i32 v[152:153], s[28:29], v148, s58, v[150:151]
	v_lshlrev_b64 v[148:149], 2, v[146:147]
	v_lshl_add_u64 v[174:175], v[152:153], 0, v[148:149]
	s_ashr_i32 s37, s36, 31
	s_lshl_b64 s[28:29], s[36:37], 21
	s_add_u32 s36, s26, s28
	s_addc_u32 s37, s27, s29
	v_ashrrev_i32_e32 v165, 31, v164
	v_lshlrev_b64 v[164:165], 12, v[164:165]
	v_lshl_add_u64 v[164:165], s[36:37], 0, v[164:165]
	v_lshl_add_u64 v[164:165], v[164:165], 0, v[148:149]
	global_load_dwordx4 v[178:181], v[174:175], off
	global_load_dwordx4 v[182:185], v[174:175], off offset:16
	global_load_dwordx4 v[186:189], v[174:175], off offset:512
	global_load_dwordx4 v[190:193], v[174:175], off offset:528
	s_mov_b64 s[28:29], 0x24000
	v_lshl_add_u64 v[154:155], v[174:175], 0, s[28:29]
	global_load_dwordx4 v[194:197], v[154:155], off
	global_load_dwordx4 v[198:201], v[154:155], off offset:16
	global_load_dwordx4 v[202:205], v[154:155], off offset:512
	global_load_dwordx4 v[206:209], v[154:155], off offset:528
	s_mov_b64 s[28:29], 0x48000
	v_lshl_add_u64 v[154:155], v[174:175], 0, s[28:29]
	global_load_dwordx4 v[210:213], v[154:155], off
	global_load_dwordx4 v[214:217], v[154:155], off offset:16
	global_load_dwordx4 v[228:231], v[154:155], off offset:512
	global_load_dwordx4 v[232:235], v[154:155], off offset:528
	s_mov_b64 s[28:29], 0x6c000
	v_lshl_add_u64 v[154:155], v[174:175], 0, s[28:29]
	global_load_dwordx4 v[236:239], v[154:155], off
	global_load_dwordx4 v[240:243], v[154:155], off offset:16
	global_load_dwordx4 v[244:247], v[154:155], off offset:512
	global_load_dwordx4 v[248:251], v[154:155], off offset:528
	s_waitcnt vmcnt(12)
	v_pk_mul_f32 v[178:179], v[178:179], 0.5 op_sel_hi:[1,0]
	v_pk_mul_f32 v[180:181], v[180:181], 0.5 op_sel_hi:[1,0]
	v_pk_mul_f32 v[178:179], v[124:125], v[178:179]
	v_pk_mul_f32 v[180:181], v[126:127], v[180:181]
	v_pk_mul_f32 v[182:183], v[182:183], 0.5 op_sel_hi:[1,0]
	v_pk_mul_f32 v[184:185], v[184:185], 0.5 op_sel_hi:[1,0]
	v_pk_mul_f32 v[182:183], v[120:121], v[182:183]
	v_pk_mul_f32 v[184:185], v[122:123], v[184:185]
	v_pk_mul_f32 v[186:187], v[186:187], 0.5 op_sel_hi:[1,0]
	v_pk_mul_f32 v[188:189], v[188:189], 0.5 op_sel_hi:[1,0]
	v_pk_mul_f32 v[186:187], v[116:117], v[186:187]
	v_pk_mul_f32 v[188:189], v[118:119], v[188:189]
	v_pk_mul_f32 v[190:191], v[190:191], 0.5 op_sel_hi:[1,0]
	v_pk_mul_f32 v[192:193], v[192:193], 0.5 op_sel_hi:[1,0]
	v_pk_mul_f32 v[190:191], v[112:113], v[190:191]
	v_pk_mul_f32 v[192:193], v[114:115], v[192:193]
	global_store_dwordx4 v[164:165], v[178:181], off
	global_store_dwordx4 v[164:165], v[182:185], off offset:16
	global_store_dwordx4 v[164:165], v[186:189], off offset:512
	global_store_dwordx4 v[164:165], v[190:193], off offset:528
	s_mov_b64 s[28:29], 0x120000
	v_lshl_add_u64 v[154:155], v[174:175], 0, s[28:29]
	global_load_dwordx4 v[124:127], v[154:155], off
	global_load_dwordx4 v[120:123], v[154:155], off offset:16
	global_load_dwordx4 v[116:119], v[154:155], off offset:512
	global_load_dwordx4 v[112:115], v[154:155], off offset:528
	s_waitcnt vmcnt(16)
	v_pk_mul_f32 v[194:195], v[194:195], 0.5 op_sel_hi:[1,0]
	v_pk_mul_f32 v[196:197], v[196:197], 0.5 op_sel_hi:[1,0]
	v_pk_mul_f32 v[194:195], v[108:109], v[194:195]
	v_pk_mul_f32 v[196:197], v[110:111], v[196:197]
	v_pk_mul_f32 v[198:199], v[198:199], 0.5 op_sel_hi:[1,0]
	v_pk_mul_f32 v[200:201], v[200:201], 0.5 op_sel_hi:[1,0]
	v_pk_mul_f32 v[198:199], v[104:105], v[198:199]
	v_pk_mul_f32 v[200:201], v[106:107], v[200:201]
	v_pk_mul_f32 v[202:203], v[202:203], 0.5 op_sel_hi:[1,0]
	v_pk_mul_f32 v[204:205], v[204:205], 0.5 op_sel_hi:[1,0]
	v_pk_mul_f32 v[202:203], v[100:101], v[202:203]
	v_pk_mul_f32 v[204:205], v[102:103], v[204:205]
	v_pk_mul_f32 v[206:207], v[206:207], 0.5 op_sel_hi:[1,0]
	v_pk_mul_f32 v[208:209], v[208:209], 0.5 op_sel_hi:[1,0]
	v_pk_mul_f32 v[206:207], v[96:97], v[206:207]
	v_pk_mul_f32 v[208:209], v[98:99], v[208:209]
	s_mov_b64 s[28:29], 0x10000
	v_lshl_add_u64 v[156:157], v[164:165], 0, s[28:29]
	global_store_dwordx4 v[156:157], v[194:197], off
	global_store_dwordx4 v[156:157], v[198:201], off offset:16
	global_store_dwordx4 v[156:157], v[202:205], off offset:512
	global_store_dwordx4 v[156:157], v[206:209], off offset:528
	s_mov_b64 s[28:29], 0x144000
	v_lshl_add_u64 v[154:155], v[174:175], 0, s[28:29]
	global_load_dwordx4 v[108:111], v[154:155], off
	global_load_dwordx4 v[104:107], v[154:155], off offset:16
	global_load_dwordx4 v[100:103], v[154:155], off offset:512
	global_load_dwordx4 v[96:99], v[154:155], off offset:528
	s_waitcnt vmcnt(20)
	v_pk_mul_f32 v[210:211], v[210:211], 0.5 op_sel_hi:[1,0]
	v_pk_mul_f32 v[212:213], v[212:213], 0.5 op_sel_hi:[1,0]
	v_pk_mul_f32 v[210:211], v[92:93], v[210:211]
	v_pk_mul_f32 v[212:213], v[94:95], v[212:213]
	v_pk_mul_f32 v[214:215], v[214:215], 0.5 op_sel_hi:[1,0]
	v_pk_mul_f32 v[216:217], v[216:217], 0.5 op_sel_hi:[1,0]
	v_pk_mul_f32 v[214:215], v[88:89], v[214:215]
	v_pk_mul_f32 v[216:217], v[90:91], v[216:217]
	v_pk_mul_f32 v[228:229], v[228:229], 0.5 op_sel_hi:[1,0]
	v_pk_mul_f32 v[230:231], v[230:231], 0.5 op_sel_hi:[1,0]
	v_pk_mul_f32 v[228:229], v[76:77], v[228:229]
	v_pk_mul_f32 v[230:231], v[78:79], v[230:231]
	v_pk_mul_f32 v[232:233], v[232:233], 0.5 op_sel_hi:[1,0]
	v_pk_mul_f32 v[234:235], v[234:235], 0.5 op_sel_hi:[1,0]
	v_pk_mul_f32 v[232:233], v[72:73], v[232:233]
	v_pk_mul_f32 v[234:235], v[74:75], v[234:235]
	s_mov_b64 s[28:29], 0x20000
	v_lshl_add_u64 v[156:157], v[164:165], 0, s[28:29]
	global_store_dwordx4 v[156:157], v[210:213], off
	global_store_dwordx4 v[156:157], v[214:217], off offset:16
	global_store_dwordx4 v[156:157], v[228:231], off offset:512
	global_store_dwordx4 v[156:157], v[232:235], off offset:528
	s_mov_b64 s[28:29], 0x168000
	v_lshl_add_u64 v[154:155], v[174:175], 0, s[28:29]
	global_load_dwordx4 v[92:95], v[154:155], off
	global_load_dwordx4 v[88:91], v[154:155], off offset:16
	global_load_dwordx4 v[76:79], v[154:155], off offset:512
	global_load_dwordx4 v[72:75], v[154:155], off offset:528
	s_waitcnt vmcnt(24)
	v_pk_mul_f32 v[236:237], v[236:237], 0.5 op_sel_hi:[1,0]
	v_pk_mul_f32 v[238:239], v[238:239], 0.5 op_sel_hi:[1,0]
	v_pk_mul_f32 v[236:237], v[84:85], v[236:237]
	v_pk_mul_f32 v[238:239], v[86:87], v[238:239]
	v_pk_mul_f32 v[240:241], v[240:241], 0.5 op_sel_hi:[1,0]
	v_pk_mul_f32 v[242:243], v[242:243], 0.5 op_sel_hi:[1,0]
	v_pk_mul_f32 v[240:241], v[80:81], v[240:241]
	v_pk_mul_f32 v[242:243], v[82:83], v[242:243]
	v_pk_mul_f32 v[244:245], v[244:245], 0.5 op_sel_hi:[1,0]
	v_pk_mul_f32 v[246:247], v[246:247], 0.5 op_sel_hi:[1,0]
	v_pk_mul_f32 v[244:245], v[68:69], v[244:245]
	v_pk_mul_f32 v[246:247], v[70:71], v[246:247]
	v_pk_mul_f32 v[248:249], v[248:249], 0.5 op_sel_hi:[1,0]
	v_pk_mul_f32 v[250:251], v[250:251], 0.5 op_sel_hi:[1,0]
	v_pk_mul_f32 v[248:249], v[64:65], v[248:249]
	v_pk_mul_f32 v[250:251], v[66:67], v[250:251]
	s_mov_b64 s[28:29], 0x30000
	v_lshl_add_u64 v[156:157], v[164:165], 0, s[28:29]
	global_store_dwordx4 v[156:157], v[236:239], off
	global_store_dwordx4 v[156:157], v[240:243], off offset:16
	global_store_dwordx4 v[156:157], v[244:247], off offset:512
	global_store_dwordx4 v[156:157], v[248:251], off offset:528
	s_mov_b64 s[28:29], 0x18c000
	v_lshl_add_u64 v[154:155], v[174:175], 0, s[28:29]
	global_load_dwordx4 v[84:87], v[154:155], off
	global_load_dwordx4 v[80:83], v[154:155], off offset:16
	global_load_dwordx4 v[68:71], v[154:155], off offset:512
	global_load_dwordx4 v[64:67], v[154:155], off offset:528
	s_waitcnt vmcnt(24)
	v_pk_mul_f32 v[124:125], v[124:125], 0.5 op_sel_hi:[1,0]
	v_pk_mul_f32 v[126:127], v[126:127], 0.5 op_sel_hi:[1,0]
	v_pk_mul_f32 v[124:125], v[60:61], v[124:125]
	v_pk_mul_f32 v[126:127], v[62:63], v[126:127]
	v_pk_mul_f32 v[120:121], v[120:121], 0.5 op_sel_hi:[1,0]
	v_pk_mul_f32 v[122:123], v[122:123], 0.5 op_sel_hi:[1,0]
	v_pk_mul_f32 v[120:121], v[56:57], v[120:121]
	v_pk_mul_f32 v[122:123], v[58:59], v[122:123]
	v_pk_mul_f32 v[116:117], v[116:117], 0.5 op_sel_hi:[1,0]
	v_pk_mul_f32 v[118:119], v[118:119], 0.5 op_sel_hi:[1,0]
	v_pk_mul_f32 v[116:117], v[44:45], v[116:117]
	v_pk_mul_f32 v[118:119], v[46:47], v[118:119]
	v_pk_mul_f32 v[112:113], v[112:113], 0.5 op_sel_hi:[1,0]
	v_pk_mul_f32 v[114:115], v[114:115], 0.5 op_sel_hi:[1,0]
	v_pk_mul_f32 v[112:113], v[40:41], v[112:113]
	v_pk_mul_f32 v[114:115], v[42:43], v[114:115]
	s_mov_b64 s[28:29], 0x80000
	v_lshl_add_u64 v[156:157], v[164:165], 0, s[28:29]
	global_store_dwordx4 v[156:157], v[124:127], off
	global_store_dwordx4 v[156:157], v[120:123], off offset:16
	global_store_dwordx4 v[156:157], v[116:119], off offset:512
	global_store_dwordx4 v[156:157], v[112:115], off offset:528
	s_waitcnt vmcnt(20)
	v_pk_mul_f32 v[108:109], v[108:109], 0.5 op_sel_hi:[1,0]
	v_pk_mul_f32 v[110:111], v[110:111], 0.5 op_sel_hi:[1,0]
	v_pk_mul_f32 v[108:109], v[52:53], v[108:109]
	v_pk_mul_f32 v[110:111], v[54:55], v[110:111]
	v_pk_mul_f32 v[104:105], v[104:105], 0.5 op_sel_hi:[1,0]
	v_pk_mul_f32 v[106:107], v[106:107], 0.5 op_sel_hi:[1,0]
	v_pk_mul_f32 v[104:105], v[48:49], v[104:105]
	v_pk_mul_f32 v[106:107], v[50:51], v[106:107]
	v_pk_mul_f32 v[100:101], v[100:101], 0.5 op_sel_hi:[1,0]
	v_pk_mul_f32 v[102:103], v[102:103], 0.5 op_sel_hi:[1,0]
	v_pk_mul_f32 v[100:101], v[36:37], v[100:101]
	v_pk_mul_f32 v[102:103], v[38:39], v[102:103]
	v_pk_mul_f32 v[96:97], v[96:97], 0.5 op_sel_hi:[1,0]
	v_pk_mul_f32 v[98:99], v[98:99], 0.5 op_sel_hi:[1,0]
	v_pk_mul_f32 v[96:97], v[32:33], v[96:97]
	v_pk_mul_f32 v[98:99], v[34:35], v[98:99]
	s_mov_b64 s[28:29], 0x90000
	v_lshl_add_u64 v[156:157], v[164:165], 0, s[28:29]
	global_store_dwordx4 v[156:157], v[108:111], off
	global_store_dwordx4 v[156:157], v[104:107], off offset:16
	global_store_dwordx4 v[156:157], v[100:103], off offset:512
	global_store_dwordx4 v[156:157], v[96:99], off offset:528
	s_waitcnt vmcnt(16)
	v_pk_mul_f32 v[92:93], v[92:93], 0.5 op_sel_hi:[1,0]
	v_pk_mul_f32 v[94:95], v[94:95], 0.5 op_sel_hi:[1,0]
	v_pk_mul_f32 v[92:93], v[28:29], v[92:93]
	v_pk_mul_f32 v[94:95], v[30:31], v[94:95]
	v_pk_mul_f32 v[88:89], v[88:89], 0.5 op_sel_hi:[1,0]
	v_pk_mul_f32 v[90:91], v[90:91], 0.5 op_sel_hi:[1,0]
	v_pk_mul_f32 v[88:89], v[24:25], v[88:89]
	v_pk_mul_f32 v[90:91], v[26:27], v[90:91]
	v_pk_mul_f32 v[76:77], v[76:77], 0.5 op_sel_hi:[1,0]
	v_pk_mul_f32 v[78:79], v[78:79], 0.5 op_sel_hi:[1,0]
	v_pk_mul_f32 v[76:77], v[20:21], v[76:77]
	v_pk_mul_f32 v[78:79], v[22:23], v[78:79]
	v_pk_mul_f32 v[72:73], v[72:73], 0.5 op_sel_hi:[1,0]
	v_pk_mul_f32 v[74:75], v[74:75], 0.5 op_sel_hi:[1,0]
	v_pk_mul_f32 v[72:73], v[12:13], v[72:73]
	v_pk_mul_f32 v[74:75], v[14:15], v[74:75]
	s_mov_b64 s[28:29], 0xa0000
	v_lshl_add_u64 v[156:157], v[164:165], 0, s[28:29]
	global_store_dwordx4 v[156:157], v[92:95], off
	global_store_dwordx4 v[156:157], v[88:91], off offset:16
	global_store_dwordx4 v[156:157], v[76:79], off offset:512
	global_store_dwordx4 v[156:157], v[72:75], off offset:528
	s_waitcnt vmcnt(12)
	v_pk_mul_f32 v[84:85], v[84:85], 0.5 op_sel_hi:[1,0]
	v_pk_mul_f32 v[86:87], v[86:87], 0.5 op_sel_hi:[1,0]
	v_pk_mul_f32 v[84:85], v[16:17], v[84:85]
	v_pk_mul_f32 v[86:87], v[18:19], v[86:87]
	v_pk_mul_f32 v[80:81], v[80:81], 0.5 op_sel_hi:[1,0]
	v_pk_mul_f32 v[82:83], v[82:83], 0.5 op_sel_hi:[1,0]
	v_pk_mul_f32 v[80:81], v[8:9], v[80:81]
	v_pk_mul_f32 v[82:83], v[10:11], v[82:83]
	v_pk_mul_f32 v[68:69], v[68:69], 0.5 op_sel_hi:[1,0]
	v_pk_mul_f32 v[70:71], v[70:71], 0.5 op_sel_hi:[1,0]
	v_pk_mul_f32 v[68:69], v[4:5], v[68:69]
	v_pk_mul_f32 v[70:71], v[6:7], v[70:71]
	v_pk_mul_f32 v[64:65], v[64:65], 0.5 op_sel_hi:[1,0]
	v_pk_mul_f32 v[66:67], v[66:67], 0.5 op_sel_hi:[1,0]
	v_pk_mul_f32 v[64:65], v[0:1], v[64:65]
	v_pk_mul_f32 v[66:67], v[2:3], v[66:67]
	s_mov_b64 s[28:29], 0xb0000
	v_lshl_add_u64 v[156:157], v[164:165], 0, s[28:29]
	global_store_dwordx4 v[156:157], v[84:87], off
	global_store_dwordx4 v[156:157], v[80:83], off offset:16
	global_store_dwordx4 v[156:157], v[68:71], off offset:512
	global_store_dwordx4 v[156:157], v[64:67], off offset:528
	s_cbranch_execz .LBB0_1330
